# sparse attention: each task prologue also requests the next task's block-list word, so the list and the first tile requests no longer wait for a load round trip
# baseline (speedup 1.0000x reference)
.LBB0_2063:
	s_or_b64 exec, exec, s[0:1]
	s_cmpk_gt_i32 s90, 0x3ff
	v_readlane_b32 s68, v251, 50
	v_readlane_b32 s69, v251, 51
	s_waitcnt lgkmcnt(0)
	s_barrier
	s_cbranch_scc1 .LBB0_2167
	v_readlane_b32 s0, v251, 7
	v_and_b32_e32 v112, 15, v152
	v_lshrrev_b32_e32 v113, 4, v152
	s_nop 1
	s_and_b32 s34, s0, 3
	s_lshr_b32 s35, s0, 2
	v_lshrrev_b32_e32 v220, 3, v153
	v_and_b32_e32 v221, 7, v153
	v_and_b32_e32 v222, 7, v220
	v_xor_b32_e32 v222, v222, v221
	v_lshlrev_b32_e32 v222, 4, v222
	v_lshl_add_u32 v114, v220, 7, v222
	v_mul_u32_u24_e32 v123, 0x90, v220
	v_lshl_add_u32 v123, v221, 4, v123
	v_add_u32_e32 v123, 0x2400, v123
	v_mul_u32_u24_e32 v117, 0x600, v220
	v_lshl_add_u32 v117, v221, 4, v117
	v_lshlrev_b32_e32 v118, 12, v220
	v_lshl_add_u32 v118, v221, 4, v118
	v_mul_u32_u24_e32 v116, 0x90, v112
	v_lshl_add_u32 v116, v113, 3, v116
	v_and_b32_e32 v222, 7, v112
	v_xor_b32_e32 v222, v222, v113
	v_lshlrev_b32_e32 v222, 4, v222
	v_lshl_add_u32 v115, v112, 7, v222
	v_xor_b32_e32 v122, 64, v115
	s_lshl_b32 s1, s0, 13
	s_add_i32 s1, s1, 0x9000
	v_lshl_add_u32 v250, v152, 4, s1
	v_mov_b32_e32 v226, 0xf149f2ca
	v_mov_b32_e32 v227, 0xff61b1e6
	v_mov_b32_e32 v203, 0x41000000
	v_mov_b32_e32 v238, 0
	v_mov_b32_e32 v224, 0xff800000
	s_mov_b32 s26, s90
	s_mov_b32 s50, 0
	s_lshr_b32 s3, s26, 8
	s_and_b32 s1, s26, 255
	s_and_b32 s2, s1, 7
	s_lshr_b32 s1, s1, 3
	s_lshl_b32 s2, s2, 5
	s_or_b32 s1, s1, s2
	s_and_b32 s4, s1, 31
	s_sub_i32 s2, 31, s4
	s_bitcmp1_b32 s3, 0
	s_cselect_b32 s4, s2, s4
	s_lshr_b32 s1, s1, 5
	s_lshl_b32 s2, s3, 3
	s_add_i32 s1, s1, s2
	s_lshl_b32 s1, s1, 11
	s_lshl_b32 s4, s4, 6
	s_add_i32 s1, s1, s4
	v_add_u32_e32 v221, s1, v152
	v_lshlrev_b32_e32 v221, 2, v221
	s_add_u32 s4, s96, 0x2e00000
	s_addc_u32 s5, s97, 0
	global_load_dword v234, v221, s[4:5]
	s_waitcnt vmcnt(0)
.Lnsa_task:
	s_lshr_b32 s65, s26, 8
	s_and_b32 s1, s26, 255
	s_and_b32 s2, s1, 7
	s_lshr_b32 s1, s1, 3
	s_lshl_b32 s2, s2, 5
	s_or_b32 s1, s1, s2
	s_and_b32 s28, s1, 31
	s_sub_i32 s2, 31, s28
	s_bitcmp1_b32 s65, 0
	s_cselect_b32 s28, s2, s28
	s_lshr_b32 s29, s1, 5
	s_lshl_b32 s2, s65, 3
	s_add_i32 s29, s29, s2
	s_lshr_b32 s30, s29, 1
	s_and_b32 s31, s29, 1
	s_lshl_b32 s36, s31, 2
	s_add_i32 s36, s36, s34
	s_lshl_b32 s33, s28, 6
	s_mov_b32 s32, s28
	s_lshl_b32 s2, s35, 5
	s_add_i32 s2, s2, s33
	v_add_u32_e32 v86, s2, v112
	v_add_u32_e32 v87, 16, v86
	v_mov_b32_e32 v243, v234
	s_nop 1
	v_or_b32_dpp v243, v243, v243 quad_perm:[1,0,3,2] row_mask:0xf bank_mask:0xf bound_ctrl:1
	s_nop 1
	v_or_b32_dpp v243, v243, v243 quad_perm:[2,3,0,1] row_mask:0xf bank_mask:0xf bound_ctrl:1
	s_nop 1
	v_or_b32_dpp v243, v243, v243 row_ror:4 row_mask:0xf bank_mask:0xf bound_ctrl:1
	s_nop 1
	v_or_b32_dpp v243, v243, v243 row_ror:8 row_mask:0xf bank_mask:0xf bound_ctrl:1
	v_mov_b32_e32 v242, v243
	s_nop 1
	v_permlane16_swap_b32_e32 v243, v242
	v_or_b32_e32 v243, v243, v242
	v_mov_b32_e32 v242, v243
	s_nop 1
	v_permlane32_swap_b32_e32 v243, v242
	v_or_b32_e32 v243, v243, v242
	s_nop 0
	v_readfirstlane_b32 s39, v243
	s_lshl_b32 s3, s30, 11
	v_add_u32_e32 v220, s3, v86
	v_lshlrev_b32_e32 v234, 10, v220
	s_lshl_b32 s4, s36, 7
	v_add_u32_e32 v234, s4, v234
	v_lshl_add_u32 v234, v113, 4, v234
	v_mov_b32_e32 v235, 0
	s_add_u32 s4, s96, 0xe000000
	s_addc_u32 s5, s97, 0
	v_lshl_add_u64 v[234:235], s[4:5], 0, v[234:235]
	global_load_dwordx4 v[160:163], v[234:235], off
	global_load_dwordx4 v[164:167], v[234:235], off offset:64
	v_lshlrev_b32_e32 v236, 8, v86
	v_lshl_add_u32 v236, v113, 6, v236
	s_add_u32 s4, s96, 0x2c00000
	s_addc_u32 s5, s97, 0
	global_load_dwordx4 v[124:127], v236, s[4:5] offset:0
	global_load_dwordx4 v[128:131], v236, s[4:5] offset:16
	global_load_dwordx4 v[132:135], v236, s[4:5] offset:32
	global_load_dwordx4 v[136:139], v236, s[4:5] offset:48
	s_lshl_b32 s6, s29, 11
	v_add_u32_e32 v221, s6, v86
	v_lshlrev_b32_e32 v221, 2, v221
	s_add_u32 s4, s96, 0x2e00000
	s_addc_u32 s5, s97, 0
	global_load_dword v84, v221, s[4:5]
	v_add_u32_e32 v220, s3, v87
	v_lshlrev_b32_e32 v234, 10, v220
	s_lshl_b32 s4, s36, 7
	v_add_u32_e32 v234, s4, v234
	v_lshl_add_u32 v234, v113, 4, v234
	v_mov_b32_e32 v235, 0
	s_add_u32 s4, s96, 0xe000000
	s_addc_u32 s5, s97, 0
	v_lshl_add_u64 v[234:235], s[4:5], 0, v[234:235]
	global_load_dwordx4 v[168:171], v[234:235], off
	global_load_dwordx4 v[172:175], v[234:235], off offset:64
	v_lshlrev_b32_e32 v236, 8, v87
	v_lshl_add_u32 v236, v113, 6, v236
	s_add_u32 s4, s96, 0x2c00000
	s_addc_u32 s5, s97, 0
	global_load_dwordx4 v[140:143], v236, s[4:5] offset:0
	global_load_dwordx4 v[144:147], v236, s[4:5] offset:16
	global_load_dwordx4 v[148:151], v236, s[4:5] offset:32
	global_load_dwordx4 v[154:157], v236, s[4:5] offset:48
	s_lshl_b32 s6, s29, 11
	v_add_u32_e32 v221, s6, v87
	v_lshlrev_b32_e32 v221, 2, v221
	s_add_u32 s4, s96, 0x2e00000
	s_addc_u32 s5, s97, 0
	global_load_dword v85, v221, s[4:5]
	s_lshl_b32 s3, s30, 11
	s_mul_i32 s2, s36, 6
	s_add_i32 s2, s2, 2
	s_add_u32 s8, s96, 0x13000000
	s_addc_u32 s9, s97, 0
	v_add_u32_e32 v223, s3, v86
	v_lshlrev_b32_e32 v223, 6, v223
	v_add_u32_e32 v223, s2, v223
	global_load_ushort v119, v223, s[8:9]
	global_load_ushort v158, v223, s[8:9] offset:2
	v_add_u32_e32 v223, s3, v87
	v_lshlrev_b32_e32 v223, 6, v223
	v_add_u32_e32 v223, s2, v223
	global_load_ushort v159, v223, s[8:9]
	global_load_ushort v233, v223, s[8:9] offset:2
	s_add_u32 s8, s96, 0x9000000
	s_addc_u32 s9, s97, 0
	v_add_u32_e32 v223, s3, v86
	v_lshlrev_b32_e32 v223, 10, v223
	s_lshl_b32 s2, s36, 7
	v_add_u32_e32 v223, s2, v223
	v_lshl_add_u32 v223, v113, 3, v223
	global_load_dwordx2 v[16:17], v223, s[8:9] offset:0
	global_load_dwordx2 v[20:21], v223, s[8:9] offset:32
	global_load_dwordx2 v[24:25], v223, s[8:9] offset:64
	global_load_dwordx2 v[28:29], v223, s[8:9] offset:96
	v_add_u32_e32 v223, s3, v87
	v_lshlrev_b32_e32 v223, 10, v223
	s_lshl_b32 s2, s36, 7
	v_add_u32_e32 v223, s2, v223
	v_lshl_add_u32 v223, v113, 3, v223
	global_load_dwordx2 v[32:33], v223, s[8:9] offset:0
	global_load_dwordx2 v[36:37], v223, s[8:9] offset:32
	global_load_dwordx2 v[40:41], v223, s[8:9] offset:64
	global_load_dwordx2 v[44:45], v223, s[8:9] offset:96
	s_mul_i32 s2, s30, 0x300000
	s_add_u32 s8, s96, 0x10000000
	s_addc_u32 s9, s97, 0
	s_add_u32 s8, s8, s2
	s_addc_u32 s9, s9, 0
	s_lshl_b32 s2, s31, 7
	s_add_u32 s8, s8, s2
	s_addc_u32 s9, s9, 0
	s_add_u32 s10, s8, 0x200
	s_addc_u32 s11, s9, 0
	global_load_dwordx4 v[88:91], v117, s[10:11]
	s_lshl_b32 s2, s29, 18
	s_add_u32 s10, s96, 0x1b200000
	s_addc_u32 s11, s97, 0
	s_add_u32 s10, s10, s2
	s_addc_u32 s11, s11, 0
	global_load_dwordx4 v[92:95], v118, s[10:11]
	s_add_i32 s12, s32, -8
	s_max_i32 s12, s12, 0
	s_mul_i32 s13, s12, 0x18000
	s_add_u32 s10, s8, 0x400
	s_addc_u32 s11, s9, 0
	s_add_u32 s10, s10, s13
	s_addc_u32 s11, s11, 0
	global_load_dwordx4 v[192:195], v117, s[10:11]
	s_lshl_b32 s13, s12, 7
	s_add_u32 s10, s96, 0x1ba00000
	s_addc_u32 s11, s97, 0
	s_add_u32 s10, s10, s2
	s_addc_u32 s11, s11, 0
	s_add_u32 s10, s10, s13
	s_addc_u32 s11, s11, 0
	global_load_dwordx4 v[196:199], v118, s[10:11]
	s_add_i32 s12, s26, s92
	s_cmpk_lt_i32 s12, 0x400
	s_cselect_b32 s12, s12, s26
	s_lshr_b32 s3, s12, 8
	s_and_b32 s1, s12, 255
	s_and_b32 s2, s1, 7
	s_lshr_b32 s1, s1, 3
	s_lshl_b32 s2, s2, 5
	s_or_b32 s1, s1, s2
	s_and_b32 s4, s1, 31
	s_sub_i32 s2, 31, s4
	s_bitcmp1_b32 s3, 0
	s_cselect_b32 s4, s2, s4
	s_lshr_b32 s1, s1, 5
	s_lshl_b32 s2, s3, 3
	s_add_i32 s1, s1, s2
	s_lshl_b32 s1, s1, 11
	s_lshl_b32 s4, s4, 6
	s_add_i32 s1, s1, s4
	v_add_u32_e32 v221, s1, v152
	v_lshlrev_b32_e32 v221, 2, v221
	s_add_u32 s4, s96, 0x2e00000
	s_addc_u32 s5, s97, 0
	global_load_dword v234, v221, s[4:5]
	s_add_u32 s46, s8, 0x200
	s_addc_u32 s47, s9, 0
	s_lshl_b32 s2, s29, 18
	s_add_u32 s48, s96, 0x1b200000
	s_addc_u32 s49, s97, 0
	s_add_u32 s48, s48, s2
	s_addc_u32 s49, s49, 0
	s_lshl_b32 s2, 2, s32
	s_add_i32 s2, s2, -1
	s_and_b32 s38, s39, s2
	s_ff1_i32_b32 s15, s38
	s_add_i32 s65, s38, -1
	s_and_b32 s38, s38, s65
	s_ff1_i32_b32 s41, s38
	s_add_i32 s65, s38, -1
	s_and_b32 s38, s38, s65
	s_ff1_i32_b32 s42, s38
	s_add_i32 s65, s38, -1
	s_and_b32 s38, s38, s65
	s_cmp_eq_u32 s15, 0
	s_cbranch_scc1 .Lnsa_e0_1
	s_mov_b32 s40, s15
	s_max_i32 s65, s40, 0
	s_mul_i32 s56, s65, 0x18000
	s_lshl_b32 s58, s65, 7
	s_add_u32 s56, s46, s56
	s_addc_u32 s57, s47, 0
	s_add_u32 s58, s48, s58
	s_addc_u32 s59, s49, 0
	global_load_dwordx4 v[88:91], v117, s[56:57]
	global_load_dwordx4 v[92:95], v118, s[58:59]
